# M3/AP balance: the 16 workgroups that also run a context-attention item leave their third-round HGRN-c item (r 496..511) to 16 more AP-phase side workgroups (32 side workgroups take r 496..527)
# speedup vs baseline: 1.0023x; 1.0023x over previous
; __device__ __forceinline__ unsigned xb_ld(unsigned* p)              { return __hip_atomic_load(p, __ATOMIC_RELAXED, __HIP_MEMORY_SCOPE_AGENT); }
; __global__ void __launch_bounds__(512, 2) mega(Params p) {
;     ...
;     bool fusedN = (G == 256);
;     { unsigned* bar_ = (unsigned*)(ws + WS_CTL); int nxc = 0;
;       for (int q_ = 0; q_ < 16; ++q_) { const unsigned c_ = xb_ld(&bar_[XB_XCNT(q_)]); if (c_) { ++nxc; if (c_ != 32u || q_ >= 8) fusedN = false; } }
;       if (nxc != 8) fusedN = false; }
.LBB0_41:
	s_or_b64 exec, exec, s[0:1]
	v_mov_b32_e32 v0, 0x22dc0000
	s_barrier
	global_load_dword v1, v0, s[58:59] offset:1280 sc1
	global_load_dword v2, v0, s[58:59] offset:1536 sc1
	global_load_dword v3, v0, s[58:59] offset:1792 sc1
	global_load_dword v4, v0, s[58:59] offset:2048 sc1
	global_load_dword v5, v0, s[58:59] offset:2304 sc1
	global_load_dword v6, v0, s[58:59] offset:2560 sc1
	global_load_dword v7, v0, s[58:59] offset:2816 sc1
	v_mov_b32_e32 v8, 0x22dc1000
	global_load_dword v9, v0, s[58:59] offset:3072 sc1
	global_load_dword v10, v0, s[58:59] offset:3328 sc1
	global_load_dword v11, v0, s[58:59] offset:3584 sc1
	global_load_dword v12, v0, s[58:59] offset:3840 sc1
	global_load_dword v13, v8, s[58:59] sc1
	global_load_dword v14, v8, s[58:59] offset:256 sc1
	global_load_dword v15, v8, s[58:59] offset:512 sc1
	global_load_dword v16, v8, s[58:59] offset:768 sc1
	global_load_dword v17, v8, s[58:59] offset:1024 sc1
	s_add_u32 s88, s58, 0xa000000
	s_addc_u32 s89, s59, 0
	s_add_u32 s40, s58, 0xe200000
	s_addc_u32 s41, s59, 0
	s_add_u32 s78, s58, 0x10300000
	s_addc_u32 s79, s59, 0
	s_add_u32 s24, s58, 0x18808000
	s_addc_u32 s25, s59, 0
	s_add_u32 s0, s58, 0x1a908000
	s_addc_u32 s1, s59, 0
	s_add_u32 s28, s58, 0x1eb08000
	v_writelane_b32 v251, s0, 42
	s_addc_u32 s29, s59, 0
	s_mov_b64 s[94:95], s[58:59]
	v_writelane_b32 v251, s1, 43
	s_add_u32 s0, s58, 0x22d08000
	s_addc_u32 s1, s59, 0
	s_cmpk_eq_i32 s96, 0x100
	s_cselect_b64 s[34:35], -1, 0
	s_mov_b64 s[92:93], s[56:57]
	s_add_u32 s56, s94, 0x22dc0500
	s_addc_u32 s57, s95, 0
	v_writelane_b32 v251, s0, 44
	v_cndmask_b32_e64 v0, 0, 1, s[34:35]
	s_mov_b32 s85, 0
	v_writelane_b32 v251, s1, 45
	s_mov_b64 s[90:91], s[54:55]
	s_mov_b64 s[52:53], s[92:93]
	s_mov_b64 s[54:55], s[94:95]
	s_mov_b32 s43, s85
	s_mul_i32 s97, s97, s96
	s_mul_i32 s97, s97, s23
	v_mov_b32_e32 v165, 0
	v_mov_b32_e32 v179, 0x358637bd
	v_mov_b32_e32 v180, 1
	v_mov_b32_e32 v183, 0x41b17218
	s_movk_i32 s93, 0x4080
	s_movk_i32 s82, 0x6000
	s_mov_b32 s71, 0xffff0000
	s_mov_b32 s73, 0x7f800000
	s_mov_b64 s[76:77], 0x80
	s_mov_b32 s92, 0x3f07dc22
	s_mov_b32 s72, 0x3f35f0e3
	s_mov_b32 s70, 0xbe11a98e
	s_waitcnt vmcnt(15)
	v_cmp_eq_u32_e32 vcc, 32, v1
	s_and_b64 s[30:31], vcc, s[34:35]
	s_waitcnt vmcnt(14)
	v_cmp_ne_u32_e64 s[4:5], 0, v2
	v_cndmask_b32_e64 v8, 0, 1, s[30:31]
	v_cmp_ne_u32_e32 vcc, 0, v1
	v_cmp_eq_u32_e64 s[0:1], 32, v2
	v_cndmask_b32_e64 v2, 0, 1, s[4:5]
	v_cndmask_b32_e32 v0, v0, v8, vcc
	v_addc_co_u32_e32 v1, vcc, 0, v2, vcc
	v_and_b32_e32 v2, 1, v0
	s_add_u32 s58, s94, 0x22dc0600
	v_cmp_eq_u32_e32 vcc, 1, v2
	s_addc_u32 s59, s95, 0
	s_and_b64 s[0:1], s[0:1], vcc
	v_cndmask_b32_e64 v2, 0, 1, s[0:1]
	v_cndmask_b32_e64 v0, v0, v2, s[4:5]
	v_and_b32_e32 v2, 1, v0
	s_waitcnt vmcnt(13)
	v_cmp_eq_u32_e64 s[6:7], 32, v3
	s_add_u32 s30, s94, 0x22dc0700
	v_cmp_eq_u32_e32 vcc, 1, v2
	s_addc_u32 s31, s95, 0
	s_and_b64 s[0:1], s[6:7], vcc
	v_cmp_ne_u32_e64 s[8:9], 0, v3
	v_cndmask_b32_e64 v2, 0, 1, s[0:1]
	s_waitcnt vmcnt(12)
	v_cmp_eq_u32_e64 s[10:11], 32, v4
	v_cndmask_b32_e64 v0, v0, v2, s[8:9]
	v_and_b32_e32 v2, 1, v0
	s_add_u32 s48, s94, 0x22dc0800
	v_cmp_eq_u32_e32 vcc, 1, v2
	s_addc_u32 s49, s95, 0
	s_and_b64 s[0:1], s[10:11], vcc
	v_cndmask_b32_e64 v2, 0, 1, s[0:1]
	v_cmp_ne_u32_e32 vcc, 0, v4
	v_cndmask_b32_e64 v3, 0, 1, s[8:9]
	s_waitcnt vmcnt(11)
	v_cmp_eq_u32_e64 s[12:13], 32, v5
	v_cndmask_b32_e32 v0, v0, v2, vcc
	v_addc_co_u32_e32 v1, vcc, v1, v3, vcc
	v_and_b32_e32 v2, 1, v0
	s_add_u32 s74, s94, 0x22dc0900
	v_cmp_eq_u32_e32 vcc, 1, v2
	s_addc_u32 s75, s95, 0
	s_and_b64 s[0:1], s[12:13], vcc
	v_cmp_ne_u32_e64 s[14:15], 0, v5
	v_cndmask_b32_e64 v2, 0, 1, s[0:1]
	s_add_u32 s0, s94, 0x22dc0a00
	v_cndmask_b32_e64 v0, v0, v2, s[14:15]
	v_and_b32_e32 v2, 1, v0
	s_addc_u32 s1, s95, 0
	s_waitcnt vmcnt(10)
	v_cmp_eq_u32_e64 s[16:17], 32, v6
	v_writelane_b32 v251, s0, 46
	v_cmp_eq_u32_e32 vcc, 1, v2
	v_cndmask_b32_e64 v5, 0, 1, s[14:15]
	v_writelane_b32 v251, s1, 47
	s_and_b64 s[0:1], s[16:17], vcc
	v_cndmask_b32_e64 v2, 0, 1, s[0:1]
	v_cmp_ne_u32_e32 vcc, 0, v6
	s_add_u32 s0, s94, 0x22dc0b00
	s_addc_u32 s1, s95, 0
	v_cndmask_b32_e32 v0, v0, v2, vcc
	v_addc_co_u32_e32 v1, vcc, v1, v5, vcc
	v_and_b32_e32 v2, 1, v0
	s_waitcnt vmcnt(9)
	v_cmp_eq_u32_e64 s[18:19], 32, v7
	v_writelane_b32 v251, s0, 48
	v_cmp_eq_u32_e32 vcc, 1, v2
	v_cmp_ne_u32_e64 s[20:21], 0, v7
	v_writelane_b32 v251, s1, 49
	s_and_b64 s[0:1], s[18:19], vcc
	v_cndmask_b32_e64 v2, 0, 1, s[0:1]
	s_add_u32 s0, s94, 0x22dc0c00
	v_cndmask_b32_e64 v0, v0, v2, s[20:21]
	s_addc_u32 s1, s95, 0
	v_and_b32_e32 v2, 1, v0
	v_writelane_b32 v251, s0, 50
	v_cmp_eq_u32_e32 vcc, 1, v2
	v_cndmask_b32_e64 v7, 0, 1, s[20:21]
	v_writelane_b32 v251, s1, 51
	s_waitcnt vmcnt(8)
	v_cmp_eq_u32_e64 s[0:1], 32, v9
	s_and_b64 s[0:1], s[0:1], vcc
	v_cmp_ne_u32_e32 vcc, 0, v9
	v_cndmask_b32_e64 v2, 0, 1, s[0:1]
	s_add_u32 s0, s94, 0x22dc0d00
	s_addc_u32 s1, s95, 0
	v_cndmask_b32_e32 v0, v0, v2, vcc
	v_writelane_b32 v251, s0, 52
	v_addc_co_u32_e32 v1, vcc, v1, v7, vcc
	v_and_b32_e32 v0, 1, v0
	v_writelane_b32 v251, s1, 53
	s_waitcnt vmcnt(7)
	v_cmp_ne_u32_e64 s[0:1], 0, v10
	v_cmp_eq_u32_e32 vcc, 1, v0
	s_waitcnt vmcnt(0)
; #define RETID() do { tid = tidx(); lane = tid & 63; wave = tid >> 6; gw = bid * 8 + wave; } while (0)
; __global__ void __launch_bounds__(512, 2) mega(Params p) {
;     ...
;         { const float lam = LAM[l], li1 = 1.f - LAM[4 + l]; const float* sw = p.in[15] + (size_t)l * 256;
;           const int nrow = (l < 3) ? TT : TL;
;           const bool side = (l < 3) && (G >= 32);
;           const int apn = side ? (G - 16) * 8 : ngw;
;           if (side && bid >= G - 16) { RETID(); const int r = 512 + (bid - (G - 16)); hgrn_c_item(P, LB + (size_t)l * 512, LB + (size_t)(4 + l) * 512, ST, p.in[13] + (size_t)l * 128, Y, r >> 2, r & 3, L, tid); }
	v_or_b32_e32 v2, v17, v16
	v_cndmask_b32_e64 v0, 0, 1, s[0:1]
	s_add_u32 s0, s94, 0x22dc0e00
	s_addc_u32 s1, s95, 0
	v_writelane_b32 v251, s0, 54
	s_nop 1
	v_writelane_b32 v251, s1, 55
	v_cmp_ne_u32_e64 s[0:1], 0, v11
	s_nop 1
	v_addc_co_u32_e64 v0, s[0:1], v1, v0, s[0:1]
	s_add_u32 s0, s94, 0x22dc0f00
	s_addc_u32 s1, s95, 0
	v_writelane_b32 v251, s0, 56
	s_nop 1
	v_writelane_b32 v251, s1, 57
	v_cmp_ne_u32_e64 s[0:1], 0, v12
	s_nop 1
	v_cndmask_b32_e64 v1, 0, 1, s[0:1]
	s_add_u32 s0, s94, 0x22dc1000
	s_addc_u32 s1, s95, 0
	v_writelane_b32 v251, s0, 58
	s_add_u32 s36, s94, 0x22dc1100
	s_addc_u32 s37, s95, 0
	v_writelane_b32 v251, s1, 59
	v_cmp_ne_u32_e64 s[0:1], 0, v13
	s_add_u32 s68, s94, 0x22dc1200
	s_addc_u32 s69, s95, 0
	v_addc_co_u32_e64 v0, s[0:1], v0, v1, s[0:1]
	v_cmp_ne_u32_e64 s[0:1], 0, v14
	s_add_u32 s86, s94, 0x22dc1300
	s_addc_u32 s87, s95, 0
	v_cndmask_b32_e64 v1, 0, 1, s[0:1]
	v_cmp_ne_u32_e64 s[0:1], 0, v15
	s_add_u32 s80, s94, 0x22dc1400
	s_addc_u32 s81, s95, 0
	v_addc_co_u32_e64 v0, s[0:1], v0, v1, s[0:1]
	v_cmp_ne_u32_e64 s[0:1], 0, v16
	s_nop 1
	v_cndmask_b32_e64 v1, 0, 1, s[0:1]
	v_cmp_ne_u32_e64 s[0:1], 0, v17
	s_nop 1
	v_addc_co_u32_e64 v0, s[0:1], v0, v1, s[0:1]
	v_or_b32_e32 v1, v2, v15
	v_or_b32_e32 v1, v1, v14
	v_or_b32_e32 v1, v1, v13
	v_or_b32_e32 v1, v1, v12
	v_or_b32_e32 v1, v1, v11
	v_or_b32_e32 v1, v1, v10
	v_cmp_eq_u32_e64 s[0:1], 0, v1
	v_cmp_eq_u32_e64 s[4:5], 8, v0
	s_and_b64 s[0:1], s[4:5], s[0:1]
	s_and_b64 s[0:1], s[0:1], vcc
	v_writelane_b32 v251, s0, 60
	v_sub_co_u32_e64 v0, s[38:39], s2, 20
	s_nop 0
	v_writelane_b32 v251, s1, 61
	s_xor_b64 s[0:1], s[0:1], -1
	v_writelane_b32 v251, s0, 62
	s_nop 1
	v_writelane_b32 v251, s1, 63
	s_add_u32 s0, s94, 0x22dc0300
	s_addc_u32 s1, s95, 0
	v_writelane_b32 v252, s0, 0
	s_cmp_eq_u32 s22, 15
	v_readlane_b32 s12, v251, 38
	v_writelane_b32 v252, s1, 1
	s_cselect_b64 s[0:1], -1, 0
	v_writelane_b32 v252, s0, 2
	s_cmp_eq_u32 s22, 14
	v_readlane_b32 s13, v251, 39
	v_writelane_b32 v252, s1, 3
	s_cselect_b64 s[0:1], -1, 0
	v_writelane_b32 v252, s0, 4
	s_cmp_eq_u32 s22, 13
	s_nop 0
	v_writelane_b32 v252, s1, 5
	s_cselect_b64 s[0:1], -1, 0
	v_writelane_b32 v252, s0, 6
	s_cmp_eq_u32 s22, 12
	s_nop 0
	v_writelane_b32 v252, s1, 7
	s_cselect_b64 s[0:1], -1, 0
	v_writelane_b32 v252, s0, 8
	s_cmp_eq_u32 s22, 11
	s_nop 0
	v_writelane_b32 v252, s1, 9
	s_cselect_b64 s[0:1], -1, 0
	v_writelane_b32 v252, s0, 10
	s_cmp_eq_u32 s22, 10
	s_nop 0
	v_writelane_b32 v252, s1, 11
	s_cselect_b64 s[0:1], -1, 0
	v_writelane_b32 v252, s0, 12
	s_cmp_eq_u32 s22, 9
	s_nop 0
	v_writelane_b32 v252, s1, 13
	s_cselect_b64 s[0:1], -1, 0
	v_writelane_b32 v252, s0, 14
	s_cmp_eq_u32 s22, 8
	s_nop 0
	v_writelane_b32 v252, s1, 15
	s_cselect_b64 s[0:1], -1, 0
	v_writelane_b32 v252, s0, 16
	s_cmp_eq_u32 s22, 7
	s_nop 0
	v_writelane_b32 v252, s1, 17
	s_cselect_b64 s[0:1], -1, 0
	v_writelane_b32 v252, s0, 18
	s_cmp_eq_u32 s22, 6
	s_nop 0
	v_writelane_b32 v252, s1, 19
	s_cselect_b64 s[0:1], -1, 0
	v_writelane_b32 v252, s0, 20
	s_cmp_eq_u32 s22, 5
	s_nop 0
	v_writelane_b32 v252, s1, 21
	s_cselect_b64 s[0:1], -1, 0
	v_writelane_b32 v252, s0, 22
	s_cmp_eq_u32 s22, 4
	s_nop 0
	v_writelane_b32 v252, s1, 23
	s_cselect_b64 s[0:1], -1, 0
	v_writelane_b32 v252, s0, 24
	s_cmp_eq_u32 s22, 3
	s_nop 0
	v_writelane_b32 v252, s1, 25
	s_cselect_b64 s[0:1], -1, 0
	v_writelane_b32 v252, s0, 26
	s_cmp_eq_u32 s22, 2
	s_nop 0
	v_writelane_b32 v252, s1, 27
	s_cselect_b64 s[0:1], -1, 0
	v_writelane_b32 v252, s0, 28
	s_cmp_eq_u32 s22, 1
	s_nop 0
	v_writelane_b32 v252, s1, 29
	s_cselect_b64 s[0:1], -1, 0
	v_writelane_b32 v252, s0, 30
	s_cmp_eq_u32 s22, 0
	s_nop 0
	v_writelane_b32 v252, s1, 31
	s_cselect_b64 s[0:1], -1, 0
	v_writelane_b32 v252, s0, 32
	s_lshl_b32 s42, s22, 6
	s_nop 0
	v_writelane_b32 v252, s1, 33
	s_lshl_b32 s0, s22, 8
	s_add_u32 s0, s60, s0
	s_addc_u32 s1, s61, 0
	s_add_u32 s4, s0, 0x1400
	s_addc_u32 s5, s1, 0
	v_writelane_b32 v252, s4, 34
	s_add_u32 s0, s0, 0x2400
	s_addc_u32 s1, s1, 0
	v_writelane_b32 v252, s5, 35
	v_writelane_b32 v252, s0, 36
	s_mov_b64 s[60:61], s[30:31]
	s_nop 0
	v_writelane_b32 v252, s1, 37
	s_add_u32 s0, s94, 0x22dc3500
	s_addc_u32 s1, s95, 0
	v_writelane_b32 v252, s0, 38
	s_nop 1
	v_writelane_b32 v252, s1, 39
	s_add_u32 s0, s94, 0x22dc3600
	s_addc_u32 s1, s95, 0
	v_writelane_b32 v252, s0, 40
	s_cmpk_lt_i32 s2, 0x400
	s_nop 0
	v_writelane_b32 v252, s1, 41
	s_cselect_b64 s[0:1], -1, 0
	v_writelane_b32 v252, s0, 42
	s_ashr_i32 s3, s2, 31
	s_nop 0
	v_writelane_b32 v252, s1, 43
	s_lshr_b32 s0, s3, 29
	s_add_i32 s0, s2, s0
	s_ashr_i32 s11, s0, 3
	s_and_b32 s0, s0, -8
	s_sub_i32 s16, s2, s0
	s_lshl_b32 s17, s16, 7
	s_ashr_i32 s0, s96, 31
	v_writelane_b32 v252, s0, 44
	s_add_u32 s0, s94, 0x22dc3800
	v_writelane_b32 v252, s0, 45
	s_addc_u32 s0, s95, 0
	s_cmp_gt_i32 s2, 31
	v_writelane_b32 v252, s0, 46
	s_cselect_b64 s[0:1], -1, 0
	v_writelane_b32 v252, s0, 47
	s_nop 1
	v_writelane_b32 v252, s1, 48
	s_sub_i32 s0, s2, 32
	v_writelane_b32 v252, s0, 49
	s_cmpk_lt_i32 s2, 0x338
	v_readfirstlane_b32 s0, v0
	s_cselect_b64 s[4:5], -1, 0
	s_lshr_b32 s0, s0, 2
	v_writelane_b32 v252, s4, 50
	s_sub_i32 s20, 31, s0
	s_and_b32 s0, s2, 3
	v_writelane_b32 v252, s5, 51
	s_or_b32 s21, s0, 28
	s_sub_i32 s0, s96, 32
	s_add_i32 s27, s2, 12
	s_add_i32 s30, s2, 6
	v_writelane_b32 v252, s0, 52
	s_add_u32 s0, s94, 0x22dc3700
	v_writelane_b32 v252, s0, 53
	s_addc_u32 s0, s95, 0
	v_writelane_b32 v252, s0, 54
	s_lshl_b32 s0, s2, 9
	s_lshl_b32 s65, s96, 9
	v_writelane_b32 v252, s0, 55
	s_cmp_gt_i32 s96, 31
	s_movk_i32 s0, 0x410
	s_cselect_b32 s0, s0, 0x420
	s_cmp_lt_i32 s2, s0
	v_writelane_b32 v252, s0, 56
	s_cselect_b64 s[0:1], -1, 0
	v_writelane_b32 v252, s0, 57
	s_cmp_lt_i32 s96, 32
	v_mbcnt_lo_u32_b32 v0, -1, 0
	v_writelane_b32 v252, s1, 58
	s_cselect_b64 s[0:1], -1, 0
	v_writelane_b32 v252, s0, 59
	v_mbcnt_hi_u32_b32 v171, -1, v0
	v_and_b32_e32 v0, 64, v171
	v_writelane_b32 v252, s1, 60
	s_add_i32 s0, s62, 0xffffff00
	v_writelane_b32 v252, s0, 61
	s_add_i32 s0, s96, -32
	s_cmp_lt_i32 s2, s0
	s_cselect_b64 s[4:5], -1, 0
	s_sub_i32 s0, s2, s0
	v_writelane_b32 v252, s4, 62
	s_add_i32 s1, s0, 0x1f0
	v_add_u32_e32 v172, 64, v0
	v_writelane_b32 v252, s5, 63
	s_lshr_b32 s4, s1, 2
	s_and_b32 s5, s0, 3
	s_lshl_b32 s0, s4, 6
	s_lshl_b32 s6, s5, 7
	s_lshl_b32 s9, s5, 8
	v_writelane_b32 v253, s0, 0
	s_add_u32 s0, s78, s9
	s_addc_u32 s1, s79, 0
	v_writelane_b32 v253, s0, 1
	v_xor_b32_e32 v178, 1, v171
	v_xor_b32_e32 v177, 2, v171
	v_writelane_b32 v253, s1, 2
	s_lshl_b32 s0, s5, 9
	s_add_u32 s0, s12, s0
	v_writelane_b32 v253, s0, 3
	s_addc_u32 s0, s13, 0
	s_add_i32 s84, s4, 0xffffff80
	s_cmp_lt_i32 s84, 0
	s_cbranch_scc0 .Lside_n0
	s_add_i32 s84, s84, 0x84
; #define LAS __attribute__((address_space(3)))
; __device__ __forceinline__ void hgrn_c_item(const u16* P, const float* LBl0, const float* LBl1, const float* ST, const float* hnw, u16* Y, int rc, int h, LAS unsigned char* L, int tid) {
;     const int lane = tid & 63, w = tid >> 6, k = tid & 127, Is = tid >> 7;
;     const int R0 = rc < 128 ? 64 * rc : TL + 64 * (rc - 128);
.Lside_n0:
	v_writelane_b32 v253, s0, 4
	s_lshl_b64 s[0:1], s[84:85], 18
	s_add_u32 s0, s28, s0
	s_addc_u32 s1, s29, s1
	s_lshl_b32 s5, s5, 16
	s_add_u32 s0, s0, s5
	v_writelane_b32 v253, s2, 5
	s_addc_u32 s1, s1, 0
	v_readlane_b32 s83, v253, 5
	v_writelane_b32 v253, s0, 6
	s_add_u32 s5, s28, s5
	s_addc_u32 s7, s29, 0
	v_writelane_b32 v253, s1, 7
	s_sub_i32 s0, 0x107, s4
	s_ashr_i32 s1, s0, 31
	s_lshl_b64 s[0:1], s[0:1], 18
	s_add_u32 s0, s5, s0
	s_addc_u32 s1, s7, s1
	v_writelane_b32 v253, s0, 8
	s_cmpk_lt_i32 s83, 0x100
	s_mov_b32 s84, s3
	v_writelane_b32 v253, s1, 9
	s_cselect_b64 s[0:1], -1, 0
	v_writelane_b32 v253, s0, 10
	v_readlane_b32 s2, v251, 34
	v_readlane_b32 s3, v251, 35
	v_writelane_b32 v253, s1, 11
	s_add_u32 s0, s94, 0xe000000
	v_writelane_b32 v253, s0, 12
	s_addc_u32 s0, s95, 0
	v_writelane_b32 v253, s0, 13
	s_add_u32 s0, s94, 0x22dc7c00
	v_writelane_b32 v253, s0, 14
	s_addc_u32 s0, s95, 0
	v_writelane_b32 v253, s0, 15
	s_lshl_b32 s0, s22, 2
	s_ashr_i32 s8, s26, 3
	s_add_i32 s12, s8, s0
	s_ashr_i32 s13, s12, 31
	s_and_b32 s19, s26, 7
	s_lshl_b32 s18, s16, 5
	s_lshl_b32 s10, s19, 20
	s_lshl_b64 s[0:1], s[12:13], 20
	s_add_u32 s2, s2, s10
	v_writelane_b32 v253, s2, 16
	s_addc_u32 s2, s3, 0
	s_add_u32 s14, s24, s0
	s_addc_u32 s15, s25, s1
	v_writelane_b32 v253, s2, 17
	s_add_u32 s2, s14, 0x80000
	s_addc_u32 s3, s15, 0
	v_writelane_b32 v253, s2, 18
	v_xor_b32_e32 v176, 4, v171
	s_movk_i32 s4, 0x20ff
	v_writelane_b32 v253, s3, 19
	s_lshl_b32 s2, s12, 8
	s_lshl_b32 s3, s19, 8
	s_cmp_gt_i32 s12, 31
	v_writelane_b32 v253, s3, 20
	s_cselect_b32 s7, 0x1800, 0
	s_add_u32 s3, s94, 0x22dcd000
	v_writelane_b32 v253, s3, 21
	s_addc_u32 s3, s95, 0
	v_writelane_b32 v253, s3, 22
	s_lshl_b32 s3, s12, 6
	s_lshl_b32 s12, s19, 5
	v_writelane_b32 v253, s3, 23
	s_or_b32 s13, s2, s12
	v_writelane_b32 v253, s2, 24
	s_or_b32 s2, s13, 24
	s_cmp_lt_i32 s26, 4
	v_writelane_b32 v253, s2, 25
	s_cselect_b64 s[2:3], -1, 0
	s_lshl_b32 s13, s26, 3
	s_lshl_b32 s19, s22, 5
	v_writelane_b32 v253, s2, 26
	s_add_i32 s13, s13, s19
	s_mul_i32 s19, s16, 0x81
	v_writelane_b32 v253, s3, 27
	s_add_i32 s2, s13, 0x2000
	s_cmp_lt_i32 s16, 0
	s_cselect_b32 s17, s19, s17
	s_mul_i32 s16, s16, 33
	s_cselect_b32 s26, s16, s18
	s_add_i32 s16, s17, s11
	s_ashr_i32 s17, s16, 31
	s_lshr_b32 s17, s17, 24
	s_add_i32 s17, s16, s17
	s_and_b32 s18, s17, 0xffffff00
	s_sub_i32 s16, s16, s18
	s_bfe_u32 s18, s16, 0x3001c
	s_add_i32 s18, s16, s18
	s_and_b32 s19, s18, 0xfff8
	s_ashr_i32 s17, s17, 8
	s_sub_i32 s19, s16, s19
	s_lshl_b32 s17, s17, 3
	s_sext_i32_i16 s19, s19
	s_add_i32 s31, s17, s19
	s_sext_i32_i16 s17, s18
	s_ashr_i32 s33, s17, 3
	s_cmpk_gt_i32 s16, 0xdf
	s_cselect_b64 s[16:17], -1, 0
	s_cmp_gt_i32 s31, 28
	s_cselect_b64 s[18:19], -1, 0
	s_and_b64 s[16:17], s[16:17], s[18:19]
	s_lshl_b32 s18, s31, 2
	s_sub_i32 s18, s33, s18
	v_writelane_b32 v253, s2, 28
	s_cmpk_lt_i32 s18, 0xffa6
	s_movk_i32 s2, 0x60
	s_cselect_b32 s19, s2, 0x62
	s_add_i32 s19, s19, s18
	s_and_b64 s[16:17], s[16:17], exec
	s_cselect_b32 s46, s19, s33
	s_cselect_b32 s50, 32, s31
	s_and_b64 s[2:3], s[38:39], exec
	s_cselect_b32 s2, s27, s21
	s_cmp_lt_i32 s83, 2
	s_cselect_b32 s2, s30, s2
	s_cmp_lt_i32 s83, 20
	s_cselect_b32 s16, 32, s20
	s_cselect_b32 s17, 0, 3
	s_ashr_i32 s3, s2, 31
	s_lshl_b32 s18, s16, 20
	s_lshl_b64 s[20:21], s[2:3], 20
	s_add_u32 s30, s40, s18
	s_addc_u32 s31, s41, 0
	s_add_u32 s38, s30, 0x80000
	s_addc_u32 s39, s31, 0
	v_writelane_b32 v253, s38, 29
	s_lshl_b32 s3, s2, 8
	s_lshl_b32 s2, s2, 1
	v_writelane_b32 v253, s39, 30
	s_mov_b32 s38, 0x20002211
	s_and_b32 s2, s2, -4
	s_mov_b32 s39, 0x22003333
	v_writelane_b32 v253, s3, 31
	s_lshr_b64 s[2:3], s[38:39], s2
	s_and_b32 s2, s2, 3
	s_lshl_b32 s3, s16, 8
	s_cmp_eq_u32 s2, 3
	s_cselect_b32 s2, s17, s2
	v_writelane_b32 v253, s3, 32
	s_cmp_eq_u32 s2, 3
	v_writelane_b32 v253, s2, 33
	s_cselect_b64 s[2:3], -1, 0
	v_writelane_b32 v253, s2, 34
	s_movk_i32 s33, 0x90
	s_mov_b32 s27, 0x3f317217
	v_writelane_b32 v253, s3, 35
	s_add_i32 s2, s26, s11
	s_ashr_i32 s3, s2, 31
	s_lshr_b32 s3, s3, 26
	s_add_i32 s3, s2, s3
	s_and_b32 s11, s3, 0xffc0
	s_sub_i32 s2, s2, s11
	s_bfe_i32 s11, s2, 0x80000
	s_bfe_u32 s11, s11, 0x3000c
	s_add_i32 s11, s2, s11
	s_and_b32 s16, s11, 0xf8
	s_sub_i32 s2, s2, s16
	s_ashr_i32 s3, s3, 6
	s_bfe_i32 s11, s11, 0x80000
	s_lshl_b32 s3, s3, 3
	s_sext_i32_i16 s11, s11
	s_sext_i32_i8 s2, s2
	s_add_i32 s16, s3, s2
	s_ashr_i32 s2, s11, 3
	v_writelane_b32 v253, s2, 36
	s_lshr_b32 s2, s11, 3
; __device__ __forceinline__ unsigned xb_ld(unsigned* p)              { return __hip_atomic_load(p, __ATOMIC_RELAXED, __HIP_MEMORY_SCOPE_AGENT); }
; __device__ __forceinline__ unsigned xb_add(unsigned* p, unsigned v) { return __hip_atomic_fetch_add(p, v, __ATOMIC_RELAXED, __HIP_MEMORY_SCOPE_AGENT); }
; #define RETID() do { tid = tidx(); lane = tid & 63; wave = tid >> 6; gw = bid * 8 + wave; } while (0)
; __global__ void __launch_bounds__(512, 2) mega(Params p) {
;     ...
;         if (fusedN) { const int pm = (int)xbar.x * 4 + (myslot >> 3), pn = myslot & 7;
;           pg8::Gemm g{Y, WOUT + (size_t)l * 2048 * 2048, TL, DM, DM}; pg8::PanelOrder S{pm, pn};
;           pg8::EpiOut E{X, l == 0 ? p.in[0] : X, mod};
;           pg8::gemm_phase<pg8::EpiOut, pg8::PanelOrder, true, true>(L, g, S, E);
;           RETID();
;           asm volatile("s_waitcnt vmcnt(0)" ::: "memory"); __syncthreads();
;           if (tid == 0) { unsigned* c_ = (unsigned*)(ws + WS_CTL) + CW_NCNT + 64 * (l * 32 + pm); (void)xb_add(c_, 1u); unsigned sp = 0;
;               while (xb_ld(c_) < 8u) { __builtin_amdgcn_s_sleep(1); if (++sp > (1u << 22)) break; }
;               __builtin_amdgcn_fence(__ATOMIC_ACQUIRE, "agent"); asm volatile("s_waitcnt vmcnt(0)" ::: "memory"); }
;           __syncthreads();
;           if (l < 3) { const float* mod1 = MOD + (size_t)(l + 1) * 2 * 6144; const float* nw1 = p.in[6] + (size_t)(l + 1) * DM;
;               norm_rows(X, nw1, mod1, H, pm * 256 + pn * 32, 32, wave, lane);
;               if (myslot < 4) { split_wait((unsigned*)(ws + WS_CTL) + CW_SPLIT2 + l * 17 * 64, bst[1], tid); RETID();
;                   norm_rows(X, nw1, mod1 + 6144, H, TL + ((int)xbar.x * 4 + myslot) * 8, 8, wave, lane); } }
	s_bfe_i64 s[2:3], s[2:3], 0x100000
	s_lshl_b64 s[2:3], s[2:3], 20
	v_writelane_b32 v253, s2, 37
	s_ashr_i32 s17, s16, 31
	s_mov_b32 s26, 0x3e027906
	v_writelane_b32 v253, s3, 38
	s_mov_b32 s2, s16
	v_writelane_b32 v253, s2, 39
	s_nop 1
	v_writelane_b32 v253, s3, 40
	s_lshl_b64 s[2:3], s[16:17], 20
	s_add_u32 s2, s24, s2
	s_addc_u32 s3, s25, s3
	s_add_u32 s16, s2, 0x80000
	v_writelane_b32 v253, s2, 41
	s_addc_u32 s17, s3, 0
	s_ashr_i32 s47, s46, 31
	v_writelane_b32 v253, s3, 42
	v_writelane_b32 v253, s16, 43
	s_mov_b32 s2, s50
	s_ashr_i32 s51, s50, 31
	v_writelane_b32 v253, s17, 44
	v_writelane_b32 v253, s2, 45
	s_mov_b32 s16, s46
	s_nop 0
	v_writelane_b32 v253, s3, 46
	v_writelane_b32 v253, s16, 47
	s_lshl_b64 s[2:3], s[50:51], 20
	s_mov_b64 s[50:51], s[90:91]
	v_writelane_b32 v253, s17, 48
	s_lshl_b64 s[16:17], s[46:47], 20
	v_writelane_b32 v253, s16, 49
	s_add_u32 s2, s40, s2
	s_movk_i32 s47, 0x1000
	v_writelane_b32 v253, s17, 50
	v_writelane_b32 v253, s40, 51
	s_addc_u32 s3, s41, s3
	s_add_u32 s16, s2, 0x80000
	v_writelane_b32 v253, s41, 52
	v_writelane_b32 v253, s2, 53
	s_addc_u32 s17, s3, 0
	s_mov_b32 s91, 0x800000
	v_writelane_b32 v253, s3, 54
	v_writelane_b32 v253, s16, 55
	s_add_u32 s2, s24, s9
	s_addc_u32 s3, s25, 0
	v_writelane_b32 v253, s17, 56
	v_writelane_b32 v253, s2, 57
	s_ashr_i32 s67, s66, 31
	s_ashr_i32 s63, s62, 31
	v_writelane_b32 v253, s3, 58
	v_writelane_b32 v253, s66, 59
	s_lshl_b64 s[2:3], s[62:63], 13
	s_mov_b32 s90, 0x3e6d3388
	v_writelane_b32 v253, s67, 60
	v_writelane_b32 v253, s2, 61
	s_movk_i32 s67, 0x3000
	s_mov_b32 s66, 0x20000
	v_writelane_b32 v253, s3, 62
	s_add_u32 s2, s94, s18
	s_addc_u32 s3, s95, 0
	v_writelane_b32 v253, s2, 63
	s_add_u32 s2, s2, 0xe280080
	v_writelane_b32 v254, s3, 0
	s_addc_u32 s3, s3, 0
	v_writelane_b32 v254, s2, 1
	s_nop 1
	v_writelane_b32 v254, s3, 2
	s_add_u32 s2, s94, s20
	v_writelane_b32 v254, s20, 3
	s_addc_u32 s3, s95, s21
	s_add_u32 s2, s2, 0x100
	v_writelane_b32 v254, s21, 4
	v_writelane_b32 v254, s2, 5
	s_addc_u32 s2, s3, 0
	v_writelane_b32 v254, s2, 6
	s_add_u32 s2, s94, 0x10302810
	s_addc_u32 s3, s95, 0
	v_writelane_b32 v254, s2, 7
	s_nop 1
	v_writelane_b32 v254, s3, 8
	s_lshl_b32 s2, s83, 11
	v_writelane_b32 v254, s2, 9
	s_lshl_b32 s2, s83, 5
	v_writelane_b32 v254, s2, 10
	s_lshl_b32 s2, s96, 5
	s_add_u32 s0, s94, s0
	v_writelane_b32 v254, s2, 11
	s_addc_u32 s1, s95, s1
	v_writelane_b32 v254, s0, 12
	s_add_u32 s0, s0, 0x18888080
	v_writelane_b32 v254, s1, 13
	s_addc_u32 s1, s1, 0
	v_writelane_b32 v254, s0, 14
	s_mul_hi_i32 s3, s62, 0x4080
	s_mul_i32 s2, s62, 0x4080
	v_writelane_b32 v254, s1, 15
	v_writelane_b32 v254, s48, 16
	s_add_u32 s0, s94, s10
	s_addc_u32 s1, s95, 0
	v_writelane_b32 v254, s49, 17
	v_writelane_b32 v254, s50, 18
	v_writelane_b32 v254, s51, 19
	v_writelane_b32 v254, s52, 20
	v_writelane_b32 v254, s53, 21
	v_writelane_b32 v254, s54, 22
	v_writelane_b32 v254, s55, 23
	v_writelane_b32 v254, s42, 24
	s_add_u32 s16, s0, 0x8000100
	s_addc_u32 s17, s1, 0
	v_writelane_b32 v254, s43, 25
	s_lshl_b32 s0, s22, 10
	s_lshl_b32 s1, s8, 8
	v_writelane_b32 v254, s2, 26
	s_add_i32 s0, s0, s1
	s_add_i32 s1, s13, 0x1ff8
	v_writelane_b32 v254, s3, 27
	v_writelane_b32 v254, s1, 28
	s_xor_b64 s[2:3], s[34:35], -1
	v_writelane_b32 v254, s2, 29
	s_lshl_b32 s1, s7, 2
	s_or_b32 s0, s0, s12
	v_writelane_b32 v254, s3, 30
	v_writelane_b32 v254, s1, 31
	v_writelane_b32 v254, s0, 32
	s_add_i32 s0, s0, -8
	v_writelane_b32 v254, s0, 33
	s_add_i32 s0, 0, 0x23ff4
	v_writelane_b32 v254, s0, 34
	s_add_i32 s0, 0, 0x13200
	v_writelane_b32 v254, s0, 35
	s_add_i32 s0, 0, 0x19e00
	v_writelane_b32 v254, s0, 36
	s_add_i32 s0, 0, 0x22600
	v_writelane_b32 v254, s0, 37
	s_lshl_b32 s0, s6, 1
	v_writelane_b32 v254, s0, 38
	s_add_i32 s5, 0, 0x23ff0
	s_movk_i32 s95, 0x2000
	v_writelane_b32 v254, s1, 39
	v_writelane_b32 v254, s62, 40
	s_movk_i32 s3, 0x7fff
	s_movk_i32 s8, 0x110
	v_writelane_b32 v254, s63, 41
	v_writelane_b32 v254, s56, 42
	s_add_i32 s9, 0, 0x17a00
	s_movk_i32 s10, 0x1100
	v_writelane_b32 v254, s57, 43
	v_writelane_b32 v254, s58, 44
	s_mov_b32 s94, 0xbf3a00e3
	s_mov_b32 s2, 0xbf38aa3b
	v_writelane_b32 v254, s59, 45
	v_writelane_b32 v254, s60, 46
	s_mov_b32 s12, s85
	s_nop 0
	v_writelane_b32 v254, s61, 47
	v_writelane_b32 v254, s48, 48
	s_nop 1
	v_writelane_b32 v254, s49, 49
	v_writelane_b32 v254, s74, 50
	s_nop 1
	v_writelane_b32 v254, s75, 51
	v_writelane_b32 v254, s65, 52
	v_writelane_b32 v254, s5, 53
	v_writelane_b32 v254, s84, 54
	s_branch .LBB0_44

; #define RETID() do { tid = tidx(); lane = tid & 63; wave = tid >> 6; gw = bid * 8 + wave; } while (0)
; __global__ void __launch_bounds__(512, 2) mega(Params p) {
;     ...
;           for (int it = bid; it < 528 + ((G >= 32) ? 512 : 528); it += G) { RETID();
;               if (it < 528) { if (it < natt && !(PROBE_DUP == 5 && rep_ == 1)) {
;                   int item = it;
;                   if (it < 512 && G == 256) { const int rnd = it >> 8, wg = it & 255; item = ((wg & 7) << 6) | (rnd * 32 + (wg >> 3)); }
;                   attn_item(P, AO, (const unsigned*)(ws + WS_CTL) + CW_KMAX + l * 8, item, (char*)lds); __syncthreads(); } }
;               else { const int r = it - 528; hgrn_c_item(P, LB0, LB1, ST, p.in[13] + (size_t)l * 128, Y, r >> 2, r & 3, L, tid); } } }
.LBB0_697:
	s_add_i32 s12, s12, s96
	v_readlane_b32 s0, v252, 56
	s_cmp_gt_i32 s96, 31
	s_cbranch_scc0 .Lm3_lim
	s_add_i32 s0, s0, 0x200
	s_sub_i32 s0, s0, s19
.Lm3_lim:
	s_cmp_ge_i32 s12, s0
	s_cbranch_scc1 .LBB0_916
